# prompt band unit prologue: dropped the vmcnt(0) drains before the first K/V LDS-DMA and before the tile loop
# baseline (speedup 1.0000x reference)
; #define ATT_WAIT_BAR(n) asm volatile("s_waitcnt vmcnt(" #n ")\n\ts_barrier" ::: "memory")
; template <bool DIFF, bool FIXED, bool F32SRC> ...
;     ...
;     const int qloc = u.qloc0 + 32 * qg + q32, cq = (u.qloc0 + 32 * qg) >> 6;
;     const bool qvalid = (32 * qg + q32) < u.nq;
;     const int qrow = qvalid ? (u.qrow0 + 32 * qg + q32) : u.qrow0;
;     bf16x8 qf[4];
; #pragma unroll
;     for (int ks = 0; ks < 4; ++ks) qf[ks] = *(const bf16x8*)(Q + (size_t)qrow * PITCH + u.h * HW + sub * 64 + ks * 16 + hi * 8);
;     float mrun = mref0, lrun = 0.f; f32x16 o[NDB];
; #pragma unroll
;     for (int db = 0; db < NDB; ++db) o[db] = f32x16{};
;     unsigned kgo[NCH], vgo[NCH];
; #pragma unroll
;     for (int i = 0; i < NCH; ++i) {
;         const int piece = w * NCH + i;
;         const int krow = DIFF ? (piece * 4 + (lane >> 4)) : (piece * 8 + (lane >> 3));
;         const int kcp = DIFF ? (lane & 15) : (lane & 7);
;         const int kch = kcp ^ (DIFF ? (krow & 15) : ((krow >> 1) & 7));
;         kgo[i] = (unsigned)(krow * PITCH + kch * 8);
;         const int p = piece * 64 + lane, st = p >> 5, key = 8 * (st / NDB) + ((p & 31) >> 2), dch = (st % NDB) * 4 + (p & 3);
;         vgo[i] = (unsigned)(key * PITCH + dch * 8);
;     }
;     ...
;     const int vlane = (4 * hi + ((lane & 15) >> 2)) * 64 + ((lane >> 4) & 1) * 32 + (lane & 3) * 8;
;     const int kswz = DIFF ? (q32 & 15) : ((q32 >> 1) & 7);
;     int koff[4];
; #pragma unroll
;     for (int ks = 0; ks < 4; ++ks) koff[ks] = q32 * RB + (((sub * 8 + 2 * ks + hi) ^ kswz) << 4);
;     int j = u.jhi, buf = 0;
;     if (!F32SRC) {
;     asm volatile("s_waitcnt vmcnt(0)" ::: "memory");
;     ATT_DMA(j, 0);
;     if (j - 1 >= u.jlo) { ATT_DMA(j - 1, 1); if (NCH == 2) ATT_WAIT_BAR(4); else ATT_WAIT_BAR(2); }
;     else ATT_WAIT_BAR(0);
.LBB0_326:
	s_or_b64 exec, exec, s[10:11]
	v_mov_b32_e32 v6, v196
	s_and_b32 s10, s12, 63
	s_lshl_b32 s12, s13, 5
	s_and_b32 s18, s12, 0xffffc000
	v_readfirstlane_b32 s13, v6
	s_ashr_i32 s16, s13, 6
	s_lshl_b32 s19, s10, 8
	v_and_b32_e32 v4, 31, v6
	s_lshl_b32 s24, s16, 5
	s_lshl_b32 s11, s10, 2
	s_or_b32 s12, s18, s19
	v_or_b32_e32 v0, s24, v4
	s_movk_i32 s10, 0x100
	v_sub_u32_e64 v104, s11, 8 clamp
	s_or_b32 s29, s11, 3
	v_cmp_gt_i32_e64 s[10:11], s10, v0
	v_or_b32_e32 v0, s12, v4
	v_add_u32_e32 v0, s24, v0
	v_mov_b32_e32 v2, s12
	v_cndmask_b32_e64 v2, v2, v0, s[10:11]
	v_ashrrev_i32_e32 v3, 31, v2
	v_readlane_b32 s36, v254, 11
	v_lshlrev_b64 v[2:3], 10, v[2:3]
	v_readlane_b32 s37, v254, 12
	v_bfe_u32 v5, v6, 5, 1
	s_lshl_b32 s90, s17, 7
	v_lshl_add_u64 v[2:3], s[36:37], 0, v[2:3]
	v_lshl_add_u64 v[98:99], v[2:3], 0, s[90:91]
	v_lshlrev_b32_e32 v0, 4, v5
	v_lshl_add_u64 v[2:3], v[98:99], 0, v[0:1]
	global_load_dwordx4 v[66:69], v[2:3], off
	global_load_dwordx4 v[70:73], v[2:3], off offset:32
	global_load_dwordx4 v[74:77], v[2:3], off offset:64
	global_load_dwordx4 v[78:81], v[2:3], off offset:96
	v_mov_b32_e32 v3, s13
	s_movk_i32 s12, 0xffc0
	s_lshl_b32 s25, s29, 6
	v_bfi_b32 v3, s12, v3, v6
	s_or_b32 s12, s25, s18
	s_ashr_i32 s13, s12, 31
	s_lshl_b64 s[12:13], s[12:13], 10
	v_readlane_b32 s36, v252, 57
	v_ashrrev_i32_e32 v3, 5, v3
	v_readlane_b32 s37, v252, 58
	s_add_u32 s30, s36, s12
	v_bfe_u32 v0, v6, 3, 3
	v_lshrrev_b32_e32 v7, 31, v3
	s_addc_u32 s51, s37, s13
	v_lshl_or_b32 v0, s16, 3, v0
	v_add_u32_e32 v8, v3, v7
	s_add_u32 s50, s30, s90
	v_lshrrev_b32_e32 v2, 1, v0
	v_lshlrev_b32_e32 v7, 11, v8
	s_addc_u32 s51, s51, 0
	v_readlane_b32 s36, v252, 59
	v_xor_b32_e32 v2, v2, v6
	v_and_b32_e32 v9, 0xfffff000, v7
	v_lshlrev_b32_e32 v7, 7, v6
	v_readlane_b32 s37, v252, 60
	s_add_u32 s12, s36, s12
	v_lshlrev_b32_e32 v2, 3, v2
	v_and_b32_e32 v10, 0xe00, v7
	v_lshlrev_b32_e32 v7, 3, v6
	v_lshlrev_b32_e32 v0, 9, v0
	s_addc_u32 s13, s37, s13
	v_and_b32_e32 v7, 24, v7
	v_and_or_b32 v0, v2, 56, v0
	v_and_b32_e32 v2, 0x7fffffe, v8
	s_add_u32 s12, s12, s90
	v_sub_u32_e32 v2, v3, v2
	v_or3_b32 v3, v10, v9, v7
	s_addc_u32 s13, s13, 0
	s_lshl_b32 s30, s16, 10
	v_lshl_add_u32 v2, v2, 5, v3
	s_add_i32 s30, s30, 0
	v_mov_b32_e32 v3, v1
	v_lshl_add_u64 v[8:9], v[0:1], 1, s[50:51]
	v_lshl_add_u64 v[10:11], v[2:3], 1, s[12:13]
	s_add_i32 s12, s30, 0x2000
	s_mov_b32 m0, s30
	v_cmp_le_u32_e32 vcc, s29, v104
	global_load_lds_dwordx4 v[8:9], off
	s_mov_b32 m0, s12
	s_mov_b64 s[12:13], -1
	global_load_lds_dwordx4 v[10:11], off
	s_cbranch_vccz .LBB0_328
	s_waitcnt vmcnt(0)
	s_barrier
	s_mov_b64 s[12:13], 0

; #define LAS __attribute__((address_space(3)))
; __device__ __forceinline__ unsigned pk2(float lo, float hi) { return f2bf(lo) | (f2bf(hi) << 16); }
; #define ATT_WAIT_BAR(n) asm volatile("s_waitcnt vmcnt(" #n ")\n\ts_barrier" ::: "memory")
; template <bool DIFF, bool FIXED, bool F32SRC> ...
;     ...
;     const int vlane = (4 * hi + ((lane & 15) >> 2)) * 64 + ((lane >> 4) & 1) * 32 + (lane & 3) * 8;
;     const int kswz = DIFF ? (q32 & 15) : ((q32 >> 1) & 7);
;     int koff[4];
; #pragma unroll
;     for (int ks = 0; ks < 4; ++ks) koff[ks] = q32 * RB + (((sub * 8 + 2 * ks + hi) ^ kswz) << 4);
;     int j = u.jhi, buf = 0;
;     if (!F32SRC) {
;     asm volatile("s_waitcnt vmcnt(0)" ::: "memory");
;     ATT_DMA(j, 0);
;     if (j - 1 >= u.jlo) { ATT_DMA(j - 1, 1); if (NCH == 2) ATT_WAIT_BAR(4); else ATT_WAIT_BAR(2); }
;     else ATT_WAIT_BAR(0);
;     }
;     for (; j >= u.jlo; --j) {
;         if (F32SRC) {
; #pragma unroll
;             for (int i = 0; i < NCH; ++i) {
;                 const int c = tid + 512 * i, row = c / (HW / 8), ch = c % (HW / 8);
;                 const size_t so = (j == u.jhi) ? (size_t)min(row, 15) * PITCH + u.h * HW + ch * 8 : (size_t)(64 * j + row) * PITCH + u.h * HW + ch * 8;
;                 const float* ks_ = ((j == u.jhi) ? kn : kc) + so; const float* vs_ = ((j == u.jhi) ? vn : vc) + so;
;                 const f32x4 k0 = ((const f32x4*)ks_)[0], k1 = ((const f32x4*)ks_)[1], v0 = ((const f32x4*)vs_)[0], v1 = ((const f32x4*)vs_)[1];
;                 u32x4 kw, vw; kw.x = pk2(k0.x, k0.y); kw.y = pk2(k0.z, k0.w); kw.z = pk2(k1.x, k1.y); kw.w = pk2(k1.z, k1.w); vw.x = pk2(v0.x, v0.y); vw.y = pk2(v0.z, v0.w); vw.z = pk2(v1.x, v1.y); vw.w = pk2(v1.z, v1.w);
;                 *(LAS u32x4*)(lds + buf * BUF + row * RB + ((ch ^ (DIFF ? (row & 15) : ((row >> 1) & 7))) << 4)) = kw;
;                 *(LAS u32x4*)(lds + buf * BUF + KBUF + (row >> 3) * (NDB * 512) + (ch >> 2) * 512 + (row & 7) * 64 + (ch & 3) * 16) = vw;
;             }
;             __syncthreads();
;         } else {
;         const int b2 = (buf >= 1) ? buf - 1 : 2;
;         if (j - 2 >= u.jlo) ATT_DMA(j - 2, b2);
.LBB0_330:
	s_add_i32 s13, s24, s19
	s_cmp_lt_i32 s16, 8
	s_cselect_b64 s[16:17], -1, 0
	s_ashr_i32 s50, s13, 6
	s_lshl_b32 s25, s12, 1
	v_readlane_b32 s12, v252, 59
	v_lshrrev_b32_e32 v10, 1, v6
	v_readlane_b32 s13, v252, 60
	s_add_u32 s12, s12, s25
	v_lshrrev_b32_e32 v8, 2, v6
	v_lshlrev_b32_e32 v9, 1, v6
	v_bfe_u32 v6, v6, 1, 3
	v_bitop3_b32 v10, v5, v10, 7 bitop3:0x78
	s_addc_u32 s13, s13, 0
	v_readlane_b32 s36, v252, 57
	v_lshlrev_b32_e32 v105, 2, v5
	v_lshlrev_b32_e32 v107, 4, v10
	v_bitop3_b32 v10, v5, v6, 2 bitop3:0x36
	v_readlane_b32 s37, v252, 58
	s_add_u32 s60, s36, s25
	v_and_or_b32 v8, v8, 3, v105
	v_lshlrev_b32_e32 v108, 4, v10
	v_bitop3_b32 v10, v5, v6, 4 bitop3:0x36
	v_bitop3_b32 v5, v5, v6, 6 bitop3:0x36
	s_addc_u32 s61, s37, 0
	s_addk_i32 s24, 0xff25
	v_and_b32_e32 v9, 32, v9
	v_lshlrev_b32_e32 v110, 4, v5
	v_lshlrev_b32_e32 v5, 6, v8
	v_lshl_add_u64 v[100:101], v[0:1], 1, s[60:61]
	v_lshl_add_u64 v[102:103], v[2:3], 1, s[12:13]
	v_add_u32_e32 v0, s24, v4
	s_add_i32 s12, s18, s19
	v_mov_b32_e32 v112, 0
	v_lshlrev_b32_e32 v106, 7, v4
	v_lshlrev_b32_e32 v109, 4, v10
	v_or3_b32 v111, v5, v9, v7
	s_add_i32 s51, s50, -8
	s_add_i32 s60, s50, -3
	v_sub_u32_e32 v113, v0, v105
	s_add_i32 s18, s12, 64
	s_mov_b32 s61, 0
	v_mov_b32_e32 v114, v214
	v_mov_b32_e32 v18, 0
	v_mov_b32_e32 v19, v112
	v_mov_b32_e32 v20, v112
	v_mov_b32_e32 v21, v112
	v_mov_b32_e32 v22, v112
	v_mov_b32_e32 v23, v112
	v_mov_b32_e32 v24, v112
	v_mov_b32_e32 v25, v112
	v_mov_b32_e32 v26, v112
	v_mov_b32_e32 v27, v112
	v_mov_b32_e32 v28, v112
	v_mov_b32_e32 v29, v112
	v_mov_b32_e32 v30, v112
	v_mov_b32_e32 v31, v112
	v_mov_b32_e32 v32, v112
	v_mov_b32_e32 v33, v112
	v_mov_b32_e32 v2, v112
	v_mov_b32_e32 v3, v112
	v_mov_b32_e32 v4, v112
	v_mov_b32_e32 v5, v112
	v_mov_b32_e32 v6, v112
	v_mov_b32_e32 v7, v112
	v_mov_b32_e32 v8, v112
	v_mov_b32_e32 v9, v112
	v_mov_b32_e32 v10, v112
	v_mov_b32_e32 v11, v112
	v_mov_b32_e32 v12, v112
	v_mov_b32_e32 v13, v112
	v_mov_b32_e32 v14, v112
	v_mov_b32_e32 v15, v112
	v_mov_b32_e32 v16, v112
	v_mov_b32_e32 v17, v112
.LBB0_331:
	s_add_i32 s12, s29, -2
	v_cmp_lt_i32_e32 vcc, s12, v104
	v_cmp_ge_i32_e64 s[12:13], s12, v104
	s_cbranch_vccnz .LBB0_333
	s_ashr_i32 s19, s18, 31
	s_lshl_b64 s[24:25], s[18:19], 10
	s_lshl_b32 s19, s61, 14
	s_addk_i32 s19, 0xc000
	s_cmp_gt_i32 s61, 0
	s_cselect_b32 s19, s19, 0x8000
	s_add_i32 s19, s30, s19
	v_lshl_add_u64 v[34:35], v[100:101], 0, s[24:25]
	v_lshl_add_u64 v[36:37], v[102:103], 0, s[24:25]
	s_add_i32 s24, s19, 0x2000
	s_mov_b32 m0, s19
	s_nop 0
	global_load_lds_dwordx4 v[34:35], off
	s_mov_b32 m0, s24
	s_nop 0
	global_load_lds_dwordx4 v[36:37], off
